# nt policy: P3 stores, X f32 stores of P2/P6/P8, plus ACT stores of P1/P7
# speedup vs baseline: 1.0092x; 1.0066x over previous
; __device__ __forceinline__ unsigned cvtpk(float lo, float hi) { f32x2_t v = {lo, hi}; bf16x2_t b = __builtin_convertvector(v, bf16x2_t); return __builtin_bit_cast(unsigned, b); }
;     __device__ __forceinline__ void operator()(const pg8::f32x4 (&acc)[2][2][4][2], const pg8::Unit& u, int wr, int wc, int fr, int fq) const {
;     ...
;             for (int m = 0; m < 4; ++m) rsv[ai][m] = ss[row0 + ai * 128 + m * 16];
; #pragma unroll
;         for (int ai = 0; ai < 2; ++ai)
; #pragma unroll
;             for (int m = 0; m < 4; ++m) {
;                 const int row = row0 + ai * 128 + m * 16;
;                 const float rs = rsqrtf(rsv[ai][m] * (1.f / DM) + EPS), c1 = -rs * LOG2E, rs2 = rs * rs;
;                 u32x4 w;
; #pragma unroll
;                 for (int n = 0; n < 2; ++n) {
;                     const pg8::f32x4 g = acc[ai][0][m][n], up = acc[ai][1][m][n];
;                     float o4[4];
; #pragma unroll
;                     for (int k = 0; k < 4; ++k) o4[k] = (g[k] * up[k]) * (rs2 * __builtin_amdgcn_rcpf(1.f + __builtin_amdgcn_exp2f(g[k] * c1)));
;                     w[2 * n] = cvtpk(o4[0], o4[1]); w[2 * n + 1] = cvtpk(o4[2], o4[3]);
;                 }
;                 *(u32x4*)(O + (size_t)row * FF + col0) = w;
.LBB0_207:
	v_lshl_add_u32 v152, s4, 8, v144
	v_ashrrev_i32_e32 v153, 31, v152
	v_lshl_add_u64 v[154:155], v[152:153], 2, s[64:65]
	global_load_dword v151, v[154:155], off
	global_load_dword v168, v[154:155], off offset:64
	v_pk_mul_f32 v[158:159], v[118:119], v[126:127]
	v_pk_mul_f32 v[160:161], v[116:117], v[124:125]
	global_load_dword v173, v[154:155], off offset:128
	global_load_dword v174, v[154:155], off offset:192
	global_load_dword v175, v[154:155], off offset:512
	global_load_dword v176, v[154:155], off offset:576
	global_load_dword v126, v[154:155], off offset:640
	global_load_dword v124, v[154:155], off offset:704
	v_pk_mul_f32 v[164:165], v[112:113], v[120:121]
	v_mov_b64_e32 v[120:121], s[84:85]
	v_pk_mul_f32 v[166:167], v[110:111], v[106:107]
	v_lshl_or_b32 v156, s5, 7, v146
	v_pk_mul_f32 v[162:163], v[114:115], v[122:123]
	v_or_b32_e32 v127, 16, v152
	v_or_b32_e32 v170, 32, v152
	v_or_b32_e32 v171, 48, v152
	v_add_u32_e32 v172, 0x80, v152
	v_add_u32_e32 v125, 0x90, v152
	v_add_u32_e32 v123, 0xa0, v152
	v_add_u32_e32 v122, 0xb0, v152
	v_mad_i64_i32 v[152:153], s[4:5], v152, s46, v[120:121]
	v_ashrrev_i32_e32 v157, 31, v156
	v_pk_mul_f32 v[104:105], v[108:109], v[104:105]
	v_pk_mul_f32 v[98:99], v[102:103], v[98:99]
	v_pk_mul_f32 v[96:97], v[100:101], v[96:97]
	v_pk_mul_f32 v[90:91], v[94:95], v[90:91]
	v_pk_mul_f32 v[88:89], v[92:93], v[88:89]
	v_pk_mul_f32 v[82:83], v[86:87], v[82:83]
	v_pk_mul_f32 v[80:81], v[84:85], v[80:81]
	v_pk_mul_f32 v[74:75], v[78:79], v[74:75]
	v_pk_mul_f32 v[72:73], v[76:77], v[72:73]
	v_pk_mul_f32 v[66:67], v[70:71], v[66:67]
	v_pk_mul_f32 v[64:65], v[68:69], v[64:65]
	v_pk_mul_f32 v[58:59], v[62:63], v[58:59]
	v_pk_mul_f32 v[56:57], v[60:61], v[56:57]
	v_pk_mul_f32 v[50:51], v[54:55], v[50:51]
	v_pk_mul_f32 v[48:49], v[52:53], v[48:49]
	v_pk_mul_f32 v[42:43], v[46:47], v[42:43]
	v_pk_mul_f32 v[40:41], v[44:45], v[40:41]
	v_pk_mul_f32 v[34:35], v[38:39], v[34:35]
	v_pk_mul_f32 v[32:33], v[36:37], v[32:33]
	v_pk_mul_f32 v[26:27], v[30:31], v[26:27]
	v_pk_mul_f32 v[24:25], v[28:29], v[24:25]
	v_pk_mul_f32 v[18:19], v[22:23], v[18:19]
	v_pk_mul_f32 v[16:17], v[20:21], v[16:17]
	v_pk_mul_f32 v[10:11], v[14:15], v[10:11]
	v_pk_mul_f32 v[8:9], v[12:13], v[8:9]
	v_pk_mul_f32 v[2:3], v[6:7], v[2:3]
	v_pk_mul_f32 v[0:1], v[4:5], v[0:1]
	s_waitcnt vmcnt(0)
	v_fmamk_f32 v106, v151, 0x3a000000, v150
	v_fmamk_f32 v107, v168, 0x3a000000, v150
	v_mul_f32_e32 v151, 0x4b800000, v106
	v_cmp_gt_f32_e32 vcc, s45, v106
	v_mul_f32_e32 v154, 0x4b800000, v107
	v_cmp_gt_f32_e64 s[4:5], s45, v107
	v_cndmask_b32_e32 v106, v106, v151, vcc
	v_rsq_f32_e32 v151, v106
	v_cndmask_b32_e64 v107, v107, v154, s[4:5]
	v_rsq_f32_e32 v154, v107
	v_lshlrev_b64 v[106:107], 1, v[156:157]
	v_mul_f32_e32 v155, 0x45800000, v151
	v_cndmask_b32_e32 v151, v151, v155, vcc
	v_mul_f32_e32 v156, 0x45800000, v154
	v_cndmask_b32_e64 v155, v154, v156, s[4:5]
	v_mul_f32_e32 v157, 0xbfb8aa3b, v151
	v_mul_f32_e32 v154, v151, v151
	v_mul_f32_e32 v151, 0xbfb8aa3b, v155
	v_mul_f32_e32 v116, v116, v157
	v_mul_f32_e32 v117, v117, v157
	v_mul_f32_e32 v118, v118, v157
	v_mul_f32_e32 v119, v119, v157
	v_mul_f32_e32 v112, v112, v157
	v_mul_f32_e32 v113, v113, v157
	v_mul_f32_e32 v114, v114, v157
	v_mul_f32_e32 v115, v115, v157
	v_mul_f32_e32 v110, v110, v151
	v_exp_f32_e32 v116, v116
	v_exp_f32_e32 v117, v117
	v_exp_f32_e32 v118, v118
	v_exp_f32_e32 v119, v119
	v_exp_f32_e32 v112, v112
	v_exp_f32_e32 v113, v113
	v_exp_f32_e32 v114, v114
	v_exp_f32_e32 v115, v115
	v_exp_f32_e32 v110, v110
	v_mul_f32_e32 v156, v155, v155
	v_mul_f32_e32 v155, v108, v151
	v_mul_f32_e32 v111, v111, v151
	v_exp_f32_e32 v155, v155
	v_exp_f32_e32 v169, v111
	v_add_f32_e32 v111, 1.0, v116
	v_add_f32_e32 v116, 1.0, v117
	v_add_f32_e32 v117, 1.0, v118
	v_add_f32_e32 v118, 1.0, v119
	v_add_f32_e32 v119, 1.0, v112
	v_add_f32_e32 v168, 1.0, v113
	v_add_f32_e32 v177, 1.0, v114
	v_add_f32_e32 v178, 1.0, v115
	v_add_f32_e32 v179, 1.0, v110
	v_rcp_f32_e32 v110, v111
	v_rcp_f32_e32 v111, v116
	v_rcp_f32_e32 v112, v117
	v_rcp_f32_e32 v113, v118
	v_rcp_f32_e32 v114, v119
	v_rcp_f32_e32 v115, v168
	v_rcp_f32_e32 v116, v177
	v_rcp_f32_e32 v117, v178
	v_mul_f32_e32 v157, v109, v151
	v_exp_f32_e32 v157, v157
	v_add_f32_e32 v155, 1.0, v155
	v_pk_mul_f32 v[110:111], v[154:155], v[110:111] op_sel_hi:[0,1]
	v_pk_mul_f32 v[112:113], v[154:155], v[112:113] op_sel_hi:[0,1]
	v_pk_mul_f32 v[114:115], v[154:155], v[114:115] op_sel_hi:[0,1]
	v_pk_mul_f32 v[116:117], v[154:155], v[116:117] op_sel_hi:[0,1]
	v_pk_mul_f32 v[110:111], v[160:161], v[110:111]
	v_pk_mul_f32 v[112:113], v[158:159], v[112:113]
	v_pk_mul_f32 v[114:115], v[164:165], v[114:115]
	v_pk_mul_f32 v[116:117], v[162:163], v[116:117]
	v_lshl_add_u64 v[152:153], v[152:153], 0, v[106:107]
	v_add_f32_e32 v157, 1.0, v157
	v_cvt_pk_bf16_f32 v110, v110, v111
	v_cvt_pk_bf16_f32 v111, v112, v113
	v_cvt_pk_bf16_f32 v112, v114, v115
	v_cvt_pk_bf16_f32 v113, v116, v117
	v_rcp_f32_e32 v118, v155
	v_rcp_f32_e32 v119, v157
	global_store_dwordx4 v[152:153], v[110:113], off nt
	v_rcp_f32_e32 v168, v179
	v_pk_mul_f32 v[108:109], v[156:157], v[118:119] op_sel_hi:[0,1]
	v_add_f32_e32 v110, 1.0, v169
	v_rcp_f32_e32 v169, v110
	v_pk_mul_f32 v[104:105], v[104:105], v[108:109]
	v_pk_mul_f32 v[108:109], v[156:157], v[168:169] op_sel_hi:[0,1]
	v_pk_mul_f32 v[110:111], v[166:167], v[108:109]
	v_cvt_pk_bf16_f32 v108, v104, v105
	v_mul_f32_e32 v104, v100, v151
	v_mul_f32_e32 v105, v101, v151
	v_exp_f32_e32 v104, v104
	v_exp_f32_e32 v105, v105
	v_cvt_pk_bf16_f32 v109, v110, v111
	v_mul_f32_e32 v110, v102, v151
	v_mul_f32_e32 v111, v103, v151
	v_exp_f32_e32 v110, v110
; __device__ __forceinline__ unsigned cvtpk(float lo, float hi) { f32x2_t v = {lo, hi}; bf16x2_t b = __builtin_convertvector(v, bf16x2_t); return __builtin_bit_cast(unsigned, b); }
;     __device__ __forceinline__ void operator()(const pg8::f32x4 (&acc)[2][2][4][2], const pg8::Unit& u, int wr, int wc, int fr, int fq) const {
;     ...
;             for (int m = 0; m < 4; ++m) {
;                 const int row = row0 + ai * 128 + m * 16;
;                 const float rs = rsqrtf(rsv[ai][m] * (1.f / DM) + EPS), c1 = -rs * LOG2E, rs2 = rs * rs;
;                 u32x4 w;
; #pragma unroll
;                 for (int n = 0; n < 2; ++n) {
;                     const pg8::f32x4 g = acc[ai][0][m][n], up = acc[ai][1][m][n];
;                     float o4[4];
; #pragma unroll
;                     for (int k = 0; k < 4; ++k) o4[k] = (g[k] * up[k]) * (rs2 * __builtin_amdgcn_rcpf(1.f + __builtin_amdgcn_exp2f(g[k] * c1)));
;                     w[2 * n] = cvtpk(o4[0], o4[1]); w[2 * n + 1] = cvtpk(o4[2], o4[3]);
;                 }
;                 *(u32x4*)(O + (size_t)row * FF + col0) = w;
	v_exp_f32_e32 v111, v111
	v_add_f32_e32 v104, 1.0, v104
	v_add_f32_e32 v105, 1.0, v105
	v_rcp_f32_e32 v104, v104
	v_rcp_f32_e32 v105, v105
	v_add_f32_e32 v102, 1.0, v110
	v_add_f32_e32 v103, 1.0, v111
	v_rcp_f32_e32 v102, v102
	v_rcp_f32_e32 v103, v103
	v_pk_mul_f32 v[100:101], v[156:157], v[104:105] op_sel_hi:[0,1]
	v_pk_mul_f32 v[96:97], v[96:97], v[100:101]
	v_pk_mul_f32 v[100:101], v[156:157], v[102:103] op_sel_hi:[0,1]
	v_cvt_pk_bf16_f32 v110, v96, v97
	v_fmamk_f32 v96, v173, 0x3a000000, v150
	v_mul_f32_e32 v97, 0x4b800000, v96
	v_cmp_gt_f32_e32 vcc, s45, v96
	v_pk_mul_f32 v[98:99], v[98:99], v[100:101]
	s_nop 0
	v_cndmask_b32_e32 v96, v96, v97, vcc
	v_cvt_pk_bf16_f32 v111, v98, v99
	v_rsq_f32_e32 v98, v96
	v_mad_i64_i32 v[96:97], s[4:5], v127, s46, v[120:121]
	v_lshl_add_u64 v[96:97], v[96:97], 0, v[106:107]
	global_store_dwordx4 v[96:97], v[108:111], off nt
	v_mul_f32_e32 v96, 0x45800000, v98
	v_cndmask_b32_e32 v96, v98, v96, vcc
	v_mul_f32_e32 v97, 0xbfb8aa3b, v96
	v_mul_f32_e32 v98, v92, v97
	v_mul_f32_e32 v99, v93, v97
	v_exp_f32_e32 v98, v98
	v_exp_f32_e32 v99, v99
	v_mul_f32_e32 v100, v94, v97
	v_mul_f32_e32 v101, v95, v97
	v_exp_f32_e32 v100, v100
	v_exp_f32_e32 v101, v101
	v_add_f32_e32 v98, 1.0, v98
	v_add_f32_e32 v99, 1.0, v99
	v_rcp_f32_e32 v98, v98
	v_rcp_f32_e32 v99, v99
	v_add_f32_e32 v94, 1.0, v100
	v_add_f32_e32 v95, 1.0, v101
	v_rcp_f32_e32 v94, v94
	v_rcp_f32_e32 v95, v95
	v_mul_f32_e32 v96, v96, v96
	v_pk_mul_f32 v[92:93], v[96:97], v[98:99] op_sel_hi:[0,1]
	v_pk_mul_f32 v[88:89], v[88:89], v[92:93]
	v_pk_mul_f32 v[92:93], v[96:97], v[94:95] op_sel_hi:[0,1]
	v_cvt_pk_bf16_f32 v88, v88, v89
	v_mul_f32_e32 v89, v84, v97
	v_pk_mul_f32 v[90:91], v[90:91], v[92:93]
	v_exp_f32_e32 v92, v89
	v_mul_f32_e32 v89, v85, v97
	v_exp_f32_e32 v93, v89
	v_cvt_pk_bf16_f32 v89, v90, v91
	v_add_f32_e32 v90, 1.0, v92
	v_mul_f32_e32 v92, v86, v97
	v_add_f32_e32 v91, 1.0, v93
	v_mul_f32_e32 v93, v87, v97
	v_exp_f32_e32 v92, v92
	v_exp_f32_e32 v93, v93
	v_rcp_f32_e32 v90, v90
	v_rcp_f32_e32 v91, v91
	v_add_f32_e32 v86, 1.0, v92
	v_add_f32_e32 v87, 1.0, v93
	v_rcp_f32_e32 v86, v86
	v_rcp_f32_e32 v87, v87
	v_pk_mul_f32 v[84:85], v[96:97], v[90:91] op_sel_hi:[0,1]
	v_pk_mul_f32 v[80:81], v[80:81], v[84:85]
	v_pk_mul_f32 v[84:85], v[96:97], v[86:87] op_sel_hi:[0,1]
	v_cvt_pk_bf16_f32 v90, v80, v81
	v_fmamk_f32 v80, v174, 0x3a000000, v150
	v_mul_f32_e32 v81, 0x4b800000, v80
	v_cmp_gt_f32_e32 vcc, s45, v80
	v_pk_mul_f32 v[82:83], v[82:83], v[84:85]
	s_nop 0
	v_cndmask_b32_e32 v80, v80, v81, vcc
	v_cvt_pk_bf16_f32 v91, v82, v83
	v_rsq_f32_e32 v82, v80
	v_mad_i64_i32 v[80:81], s[4:5], v170, s46, v[120:121]
	v_lshl_add_u64 v[80:81], v[80:81], 0, v[106:107]
	global_store_dwordx4 v[80:81], v[88:91], off nt
	v_mul_f32_e32 v80, 0x45800000, v82
	v_cndmask_b32_e32 v80, v82, v80, vcc
	v_mul_f32_e32 v81, 0xbfb8aa3b, v80
	v_mul_f32_e32 v82, v76, v81
	v_mul_f32_e32 v83, v77, v81
	v_exp_f32_e32 v82, v82
	v_exp_f32_e32 v83, v83
	v_mul_f32_e32 v84, v78, v81
	v_mul_f32_e32 v85, v79, v81
	v_exp_f32_e32 v84, v84
	v_exp_f32_e32 v85, v85
	v_add_f32_e32 v82, 1.0, v82
	v_add_f32_e32 v83, 1.0, v83
	v_rcp_f32_e32 v82, v82
	v_rcp_f32_e32 v83, v83
	v_add_f32_e32 v78, 1.0, v84
	v_add_f32_e32 v79, 1.0, v85
	v_rcp_f32_e32 v78, v78
	v_rcp_f32_e32 v79, v79
	v_mul_f32_e32 v80, v80, v80
	v_pk_mul_f32 v[76:77], v[80:81], v[82:83] op_sel_hi:[0,1]
	v_pk_mul_f32 v[72:73], v[72:73], v[76:77]
	v_pk_mul_f32 v[76:77], v[80:81], v[78:79] op_sel_hi:[0,1]
	v_cvt_pk_bf16_f32 v72, v72, v73
	v_mul_f32_e32 v73, v68, v81
	v_pk_mul_f32 v[74:75], v[74:75], v[76:77]
	v_exp_f32_e32 v76, v73
	v_mul_f32_e32 v73, v69, v81
	v_exp_f32_e32 v77, v73
	v_cvt_pk_bf16_f32 v73, v74, v75
	v_add_f32_e32 v74, 1.0, v76
	v_mul_f32_e32 v76, v70, v81
	v_add_f32_e32 v75, 1.0, v77
	v_mul_f32_e32 v77, v71, v81
	v_exp_f32_e32 v76, v76
	v_exp_f32_e32 v77, v77
	v_rcp_f32_e32 v74, v74
	v_rcp_f32_e32 v75, v75
	v_add_f32_e32 v70, 1.0, v76
	v_add_f32_e32 v71, 1.0, v77
	v_rcp_f32_e32 v70, v70
	v_rcp_f32_e32 v71, v71
	v_pk_mul_f32 v[68:69], v[80:81], v[74:75] op_sel_hi:[0,1]
	v_pk_mul_f32 v[64:65], v[64:65], v[68:69]
	v_pk_mul_f32 v[68:69], v[80:81], v[70:71] op_sel_hi:[0,1]
	v_cvt_pk_bf16_f32 v74, v64, v65
	v_fmamk_f32 v64, v175, 0x3a000000, v150
	v_mul_f32_e32 v65, 0x4b800000, v64
	v_cmp_gt_f32_e32 vcc, s45, v64
	v_pk_mul_f32 v[66:67], v[66:67], v[68:69]
	s_nop 0
	v_cndmask_b32_e32 v64, v64, v65, vcc
	v_cvt_pk_bf16_f32 v75, v66, v67
	v_rsq_f32_e32 v66, v64
	v_mad_i64_i32 v[64:65], s[4:5], v171, s46, v[120:121]
	v_lshl_add_u64 v[64:65], v[64:65], 0, v[106:107]
	global_store_dwordx4 v[64:65], v[72:75], off nt
	v_mul_f32_e32 v64, 0x45800000, v66
	v_cndmask_b32_e32 v64, v66, v64, vcc
	v_mul_f32_e32 v65, 0xbfb8aa3b, v64
	v_mul_f32_e32 v66, v60, v65
	v_mul_f32_e32 v67, v61, v65
	v_exp_f32_e32 v66, v66
	v_exp_f32_e32 v67, v67
	v_mul_f32_e32 v68, v62, v65
	v_mul_f32_e32 v69, v63, v65
	v_exp_f32_e32 v68, v68
	v_exp_f32_e32 v69, v69
	v_add_f32_e32 v66, 1.0, v66
	v_add_f32_e32 v67, 1.0, v67
	v_rcp_f32_e32 v66, v66
	v_rcp_f32_e32 v67, v67
	v_add_f32_e32 v62, 1.0, v68
	v_add_f32_e32 v63, 1.0, v69
	v_rcp_f32_e32 v62, v62
	v_rcp_f32_e32 v63, v63
	v_mul_f32_e32 v64, v64, v64
	v_pk_mul_f32 v[60:61], v[64:65], v[66:67] op_sel_hi:[0,1]
	v_pk_mul_f32 v[56:57], v[56:57], v[60:61]
	v_pk_mul_f32 v[60:61], v[64:65], v[62:63] op_sel_hi:[0,1]
	v_cvt_pk_bf16_f32 v56, v56, v57
	v_mul_f32_e32 v57, v52, v65
	v_pk_mul_f32 v[58:59], v[58:59], v[60:61]
	v_exp_f32_e32 v60, v57
	v_mul_f32_e32 v57, v53, v65
	v_exp_f32_e32 v61, v57
	v_cvt_pk_bf16_f32 v57, v58, v59
	v_add_f32_e32 v58, 1.0, v60
	v_mul_f32_e32 v60, v54, v65
	v_add_f32_e32 v59, 1.0, v61
; __device__ __forceinline__ unsigned cvtpk(float lo, float hi) { f32x2_t v = {lo, hi}; bf16x2_t b = __builtin_convertvector(v, bf16x2_t); return __builtin_bit_cast(unsigned, b); }
;     __device__ __forceinline__ void operator()(const pg8::f32x4 (&acc)[2][2][4][2], const pg8::Unit& u, int wr, int wc, int fr, int fq) const {
;     ...
;             for (int m = 0; m < 4; ++m) {
;                 const int row = row0 + ai * 128 + m * 16;
;                 const float rs = rsqrtf(rsv[ai][m] * (1.f / DM) + EPS), c1 = -rs * LOG2E, rs2 = rs * rs;
;                 u32x4 w;
; #pragma unroll
;                 for (int n = 0; n < 2; ++n) {
;                     const pg8::f32x4 g = acc[ai][0][m][n], up = acc[ai][1][m][n];
;                     float o4[4];
; #pragma unroll
;                     for (int k = 0; k < 4; ++k) o4[k] = (g[k] * up[k]) * (rs2 * __builtin_amdgcn_rcpf(1.f + __builtin_amdgcn_exp2f(g[k] * c1)));
;                     w[2 * n] = cvtpk(o4[0], o4[1]); w[2 * n + 1] = cvtpk(o4[2], o4[3]);
;                 }
;                 *(u32x4*)(O + (size_t)row * FF + col0) = w;
	v_mul_f32_e32 v61, v55, v65
	v_exp_f32_e32 v60, v60
	v_exp_f32_e32 v61, v61
	v_rcp_f32_e32 v58, v58
	v_rcp_f32_e32 v59, v59
	v_add_f32_e32 v54, 1.0, v60
	v_add_f32_e32 v55, 1.0, v61
	v_rcp_f32_e32 v54, v54
	v_rcp_f32_e32 v55, v55
	v_pk_mul_f32 v[52:53], v[64:65], v[58:59] op_sel_hi:[0,1]
	v_pk_mul_f32 v[48:49], v[48:49], v[52:53]
	v_pk_mul_f32 v[52:53], v[64:65], v[54:55] op_sel_hi:[0,1]
	v_cvt_pk_bf16_f32 v58, v48, v49
	v_fmamk_f32 v48, v176, 0x3a000000, v150
	v_mul_f32_e32 v49, 0x4b800000, v48
	v_cmp_gt_f32_e32 vcc, s45, v48
	v_pk_mul_f32 v[50:51], v[50:51], v[52:53]
	s_nop 0
	v_cndmask_b32_e32 v48, v48, v49, vcc
	v_cvt_pk_bf16_f32 v59, v50, v51
	v_rsq_f32_e32 v50, v48
	v_mad_i64_i32 v[48:49], s[4:5], v172, s46, v[120:121]
	v_lshl_add_u64 v[48:49], v[48:49], 0, v[106:107]
	global_store_dwordx4 v[48:49], v[56:59], off nt
	v_mul_f32_e32 v48, 0x45800000, v50
	v_cndmask_b32_e32 v48, v50, v48, vcc
	v_mul_f32_e32 v49, 0xbfb8aa3b, v48
	v_mul_f32_e32 v50, v44, v49
	v_mul_f32_e32 v51, v45, v49
	v_exp_f32_e32 v50, v50
	v_exp_f32_e32 v51, v51
	v_mul_f32_e32 v52, v46, v49
	v_mul_f32_e32 v53, v47, v49
	v_exp_f32_e32 v52, v52
	v_exp_f32_e32 v53, v53
	v_add_f32_e32 v50, 1.0, v50
	v_add_f32_e32 v51, 1.0, v51
	v_rcp_f32_e32 v50, v50
	v_rcp_f32_e32 v51, v51
	v_add_f32_e32 v46, 1.0, v52
	v_add_f32_e32 v47, 1.0, v53
	v_rcp_f32_e32 v46, v46
	v_rcp_f32_e32 v47, v47
	v_mul_f32_e32 v48, v48, v48
	v_pk_mul_f32 v[44:45], v[48:49], v[50:51] op_sel_hi:[0,1]
	v_pk_mul_f32 v[40:41], v[40:41], v[44:45]
	v_pk_mul_f32 v[44:45], v[48:49], v[46:47] op_sel_hi:[0,1]
	v_cvt_pk_bf16_f32 v40, v40, v41
	v_mul_f32_e32 v41, v36, v49
	v_pk_mul_f32 v[42:43], v[42:43], v[44:45]
	v_exp_f32_e32 v44, v41
	v_mul_f32_e32 v41, v37, v49
	v_exp_f32_e32 v45, v41
	v_cvt_pk_bf16_f32 v41, v42, v43
	v_add_f32_e32 v42, 1.0, v44
	v_mul_f32_e32 v44, v38, v49
	v_add_f32_e32 v43, 1.0, v45
	v_mul_f32_e32 v45, v39, v49
	v_exp_f32_e32 v44, v44
	v_exp_f32_e32 v45, v45
	v_rcp_f32_e32 v42, v42
	v_rcp_f32_e32 v43, v43
	v_add_f32_e32 v38, 1.0, v44
	v_add_f32_e32 v39, 1.0, v45
	v_rcp_f32_e32 v38, v38
	v_rcp_f32_e32 v39, v39
	v_pk_mul_f32 v[36:37], v[48:49], v[42:43] op_sel_hi:[0,1]
	v_pk_mul_f32 v[32:33], v[32:33], v[36:37]
	v_pk_mul_f32 v[36:37], v[48:49], v[38:39] op_sel_hi:[0,1]
	v_cvt_pk_bf16_f32 v42, v32, v33
	v_fmamk_f32 v32, v126, 0x3a000000, v150
	v_mul_f32_e32 v33, 0x4b800000, v32
	v_cmp_gt_f32_e32 vcc, s45, v32
	v_pk_mul_f32 v[34:35], v[34:35], v[36:37]
	s_nop 0
	v_cndmask_b32_e32 v32, v32, v33, vcc
	v_cvt_pk_bf16_f32 v43, v34, v35
	v_rsq_f32_e32 v34, v32
	v_mad_i64_i32 v[32:33], s[4:5], v125, s46, v[120:121]
	v_lshl_add_u64 v[32:33], v[32:33], 0, v[106:107]
	global_store_dwordx4 v[32:33], v[40:43], off nt
	v_mul_f32_e32 v32, 0x45800000, v34
	v_cndmask_b32_e32 v32, v34, v32, vcc
	v_mul_f32_e32 v33, 0xbfb8aa3b, v32
	v_mul_f32_e32 v34, v28, v33
	v_mul_f32_e32 v35, v29, v33
	v_exp_f32_e32 v34, v34
	v_exp_f32_e32 v35, v35
	v_mul_f32_e32 v36, v30, v33
	v_mul_f32_e32 v37, v31, v33
	v_exp_f32_e32 v36, v36
	v_exp_f32_e32 v37, v37
	v_add_f32_e32 v34, 1.0, v34
	v_add_f32_e32 v35, 1.0, v35
	v_rcp_f32_e32 v34, v34
	v_rcp_f32_e32 v35, v35
	v_add_f32_e32 v30, 1.0, v36
	v_add_f32_e32 v31, 1.0, v37
	v_rcp_f32_e32 v30, v30
	v_rcp_f32_e32 v31, v31
	v_mul_f32_e32 v32, v32, v32
	v_pk_mul_f32 v[28:29], v[32:33], v[34:35] op_sel_hi:[0,1]
	v_pk_mul_f32 v[24:25], v[24:25], v[28:29]
	v_pk_mul_f32 v[28:29], v[32:33], v[30:31] op_sel_hi:[0,1]
	v_cvt_pk_bf16_f32 v24, v24, v25
	v_mul_f32_e32 v25, v20, v33
	v_pk_mul_f32 v[26:27], v[26:27], v[28:29]
	v_exp_f32_e32 v28, v25
	v_mul_f32_e32 v25, v21, v33
	v_exp_f32_e32 v29, v25
	v_cvt_pk_bf16_f32 v25, v26, v27
	v_add_f32_e32 v26, 1.0, v28
	v_mul_f32_e32 v28, v22, v33
	v_add_f32_e32 v27, 1.0, v29
	v_mul_f32_e32 v29, v23, v33
	v_exp_f32_e32 v28, v28
	v_exp_f32_e32 v29, v29
	v_rcp_f32_e32 v26, v26
	v_rcp_f32_e32 v27, v27
	v_add_f32_e32 v22, 1.0, v28
	v_add_f32_e32 v23, 1.0, v29
	v_rcp_f32_e32 v22, v22
	v_rcp_f32_e32 v23, v23
	v_pk_mul_f32 v[20:21], v[32:33], v[26:27] op_sel_hi:[0,1]
	v_pk_mul_f32 v[16:17], v[16:17], v[20:21]
	v_pk_mul_f32 v[20:21], v[32:33], v[22:23] op_sel_hi:[0,1]
	v_cvt_pk_bf16_f32 v26, v16, v17
	v_fmamk_f32 v16, v124, 0x3a000000, v150
	v_mul_f32_e32 v17, 0x4b800000, v16
	v_cmp_gt_f32_e32 vcc, s45, v16
	v_pk_mul_f32 v[18:19], v[18:19], v[20:21]
	s_nop 0
	v_cndmask_b32_e32 v16, v16, v17, vcc
	v_cvt_pk_bf16_f32 v27, v18, v19
	v_rsq_f32_e32 v18, v16
	v_mad_i64_i32 v[16:17], s[4:5], v123, s46, v[120:121]
	v_lshl_add_u64 v[16:17], v[16:17], 0, v[106:107]
	global_store_dwordx4 v[16:17], v[24:27], off nt
	v_mul_f32_e32 v16, 0x45800000, v18
	v_cndmask_b32_e32 v16, v18, v16, vcc
	v_mul_f32_e32 v17, 0xbfb8aa3b, v16
	v_mul_f32_e32 v18, v12, v17
	v_mul_f32_e32 v19, v13, v17
	v_exp_f32_e32 v18, v18
	v_exp_f32_e32 v19, v19
	v_mul_f32_e32 v20, v14, v17
	v_mul_f32_e32 v21, v15, v17
	v_exp_f32_e32 v20, v20
	v_exp_f32_e32 v21, v21
	v_add_f32_e32 v18, 1.0, v18
	v_add_f32_e32 v19, 1.0, v19
	v_rcp_f32_e32 v18, v18
	v_rcp_f32_e32 v19, v19
	v_add_f32_e32 v14, 1.0, v20
	v_add_f32_e32 v15, 1.0, v21
	v_rcp_f32_e32 v14, v14
	v_rcp_f32_e32 v15, v15
	v_mul_f32_e32 v16, v16, v16
	v_pk_mul_f32 v[12:13], v[16:17], v[18:19] op_sel_hi:[0,1]
	v_pk_mul_f32 v[8:9], v[8:9], v[12:13]
	v_pk_mul_f32 v[12:13], v[16:17], v[14:15] op_sel_hi:[0,1]
	v_cvt_pk_bf16_f32 v8, v8, v9
	v_mul_f32_e32 v9, v4, v17
	v_pk_mul_f32 v[10:11], v[10:11], v[12:13]
	v_exp_f32_e32 v12, v9
	v_mul_f32_e32 v9, v5, v17
	v_exp_f32_e32 v13, v9
	v_cvt_pk_bf16_f32 v9, v10, v11
	v_add_f32_e32 v10, 1.0, v12
	v_mul_f32_e32 v12, v6, v17
	v_add_f32_e32 v11, 1.0, v13
	v_mul_f32_e32 v13, v7, v17
	v_exp_f32_e32 v12, v12
	v_exp_f32_e32 v13, v13
	v_rcp_f32_e32 v10, v10
	v_rcp_f32_e32 v11, v11
	v_add_f32_e32 v6, 1.0, v12
	v_add_f32_e32 v7, 1.0, v13
	v_rcp_f32_e32 v6, v6
	v_rcp_f32_e32 v7, v7
	v_pk_mul_f32 v[4:5], v[16:17], v[10:11] op_sel_hi:[0,1]
	v_pk_mul_f32 v[0:1], v[0:1], v[4:5]
	s_andn2_b64 vcc, exec, s[2:3]
	v_pk_mul_f32 v[4:5], v[16:17], v[6:7] op_sel_hi:[0,1]
	v_pk_mul_f32 v[2:3], v[2:3], v[4:5]
	v_cvt_pk_bf16_f32 v10, v0, v1
	v_mad_i64_i32 v[0:1], s[4:5], v122, s46, v[120:121]
	v_cvt_pk_bf16_f32 v11, v2, v3
	v_lshl_add_u64 v[0:1], v[0:1], 0, v[106:107]
	s_mov_b64 s[2:3], -1
	global_store_dwordx4 v[0:1], v[8:11], off nt
	s_cbranch_vccnz .LBB0_200
	s_andn2_b64 vcc, exec, s[8:9]
	s_cbranch_vccnz .LBB0_199
	s_barrier
	s_branch .LBB0_199

; __device__ __forceinline__ unsigned cvtpk(float lo, float hi) { f32x2_t v = {lo, hi}; bf16x2_t b = __builtin_convertvector(v, bf16x2_t); return __builtin_bit_cast(unsigned, b); }
;     __device__ __forceinline__ void operator()(const pg8::f32x4 (&acc)[2][2][4][2], const pg8::Unit& u, int wr, int wc, int fr, int fq) const {
;     ...
;             for (int m = 0; m < 4; ++m) rsv[ai][m] = ss[row0 + ai * 128 + m * 16];
; #pragma unroll
;         for (int ai = 0; ai < 2; ++ai)
; #pragma unroll
;             for (int m = 0; m < 4; ++m) {
;                 const int row = row0 + ai * 128 + m * 16;
;                 const float rs = rsqrtf(rsv[ai][m] * (1.f / DM) + EPS), c1 = -rs * LOG2E, rs2 = rs * rs;
;                 u32x4 w;
; #pragma unroll
;                 for (int n = 0; n < 2; ++n) {
;                     const pg8::f32x4 g = acc[ai][0][m][n], up = acc[ai][1][m][n];
;                     float o4[4];
; #pragma unroll
;                     for (int k = 0; k < 4; ++k) o4[k] = (g[k] * up[k]) * (rs2 * __builtin_amdgcn_rcpf(1.f + __builtin_amdgcn_exp2f(g[k] * c1)));
;                     w[2 * n] = cvtpk(o4[0], o4[1]); w[2 * n + 1] = cvtpk(o4[2], o4[3]);
;                 }
;                 *(u32x4*)(O + (size_t)row * FF + col0) = w;
.LBB0_1079:
	v_lshl_add_u32 v168, s2, 8, v159
	v_ashrrev_i32_e32 v169, 31, v168
	v_lshl_add_u64 v[170:171], v[168:169], 2, s[10:11]
	v_or_b32_e32 v144, 16, v168
	global_load_dword v184, v[170:171], off
	v_ashrrev_i32_e32 v145, 31, v144
	v_lshl_add_u64 v[166:167], v[144:145], 2, s[10:11]
	global_load_dword v185, v[166:167], off
	v_lshl_or_b32 v172, s3, 7, v161
	v_pk_mul_f32 v[174:175], v[118:119], v[126:127]
	v_pk_mul_f32 v[176:177], v[116:117], v[124:125]
	v_or_b32_e32 v126, 32, v168
	v_or_b32_e32 v124, 48, v168
	v_ashrrev_i32_e32 v173, 31, v172
	v_ashrrev_i32_e32 v127, 31, v126
	v_ashrrev_i32_e32 v125, 31, v124
	v_pk_mul_f32 v[178:179], v[114:115], v[122:123]
	v_lshlrev_b64 v[122:123], 1, v[172:173]
	v_lshl_add_u64 v[172:173], v[126:127], 2, s[10:11]
	v_lshl_add_u64 v[182:183], v[124:125], 2, s[10:11]
	global_load_dword v187, v[170:171], off offset:512
	global_load_dword v188, v[170:171], off offset:576
	global_load_dword v127, v[170:171], off offset:640
	global_load_dword v189, v[172:173], off
	global_load_dword v190, v[182:183], off
	global_load_dword v125, v[170:171], off offset:704
	v_pk_mul_f32 v[180:181], v[112:113], v[120:121]
	v_mov_b64_e32 v[120:121], s[84:85]
	v_add_u32_e32 v186, 0x80, v168
	v_add_u32_e32 v167, 0x90, v168
	v_add_u32_e32 v166, 0xa0, v168
	v_add_u32_e32 v145, 0xb0, v168
	v_mad_i64_i32 v[168:169], s[2:3], v168, s46, v[120:121]
	v_lshl_add_u64 v[168:169], v[168:169], 0, v[122:123]
	v_pk_mul_f32 v[106:107], v[110:111], v[106:107]
	v_pk_mul_f32 v[104:105], v[108:109], v[104:105]
	v_pk_mul_f32 v[98:99], v[102:103], v[98:99]
	v_pk_mul_f32 v[96:97], v[100:101], v[96:97]
	v_pk_mul_f32 v[90:91], v[94:95], v[90:91]
	v_pk_mul_f32 v[88:89], v[92:93], v[88:89]
	v_pk_mul_f32 v[82:83], v[86:87], v[82:83]
	v_pk_mul_f32 v[80:81], v[84:85], v[80:81]
	v_pk_mul_f32 v[74:75], v[78:79], v[74:75]
	v_pk_mul_f32 v[72:73], v[76:77], v[72:73]
	v_pk_mul_f32 v[66:67], v[70:71], v[66:67]
	v_pk_mul_f32 v[64:65], v[68:69], v[64:65]
	v_pk_mul_f32 v[58:59], v[62:63], v[58:59]
	v_pk_mul_f32 v[56:57], v[60:61], v[56:57]
	v_pk_mul_f32 v[50:51], v[54:55], v[50:51]
	v_pk_mul_f32 v[48:49], v[52:53], v[48:49]
	v_pk_mul_f32 v[42:43], v[46:47], v[42:43]
	v_pk_mul_f32 v[40:41], v[44:45], v[40:41]
	v_pk_mul_f32 v[34:35], v[38:39], v[34:35]
	v_pk_mul_f32 v[32:33], v[36:37], v[32:33]
	v_pk_mul_f32 v[26:27], v[30:31], v[26:27]
	v_pk_mul_f32 v[24:25], v[28:29], v[24:25]
	v_pk_mul_f32 v[18:19], v[22:23], v[18:19]
	v_pk_mul_f32 v[16:17], v[20:21], v[16:17]
	v_pk_mul_f32 v[10:11], v[14:15], v[10:11]
	v_pk_mul_f32 v[8:9], v[12:13], v[8:9]
	v_pk_mul_f32 v[2:3], v[6:7], v[2:3]
	v_pk_mul_f32 v[0:1], v[4:5], v[0:1]
	s_waitcnt vmcnt(0)
	v_fmamk_f32 v170, v184, 0x3a000000, v165
	v_mul_f32_e32 v171, 0x4b800000, v170
	v_cmp_gt_f32_e32 vcc, s45, v170
	v_fmamk_f32 v172, v185, 0x3a000000, v165
	v_cmp_gt_f32_e64 s[2:3], s45, v172
	v_cndmask_b32_e32 v170, v170, v171, vcc
	v_mul_f32_e32 v171, 0x4b800000, v172
	v_rsq_f32_e32 v170, v170
	v_cndmask_b32_e64 v171, v172, v171, s[2:3]
	v_rsq_f32_e32 v171, v171
	v_mul_f32_e32 v172, 0x45800000, v170
	v_cndmask_b32_e32 v170, v170, v172, vcc
	v_mul_f32_e32 v172, 0x45800000, v171
	v_mul_f32_e32 v173, 0xbfb8aa3b, v170
	v_cndmask_b32_e64 v171, v171, v172, s[2:3]
	v_mul_f32_e32 v172, v116, v173
	v_mul_f32_e32 v117, v117, v173
	v_mul_f32_e32 v118, v118, v173
	v_mul_f32_e32 v119, v119, v173
	v_mul_f32_e32 v112, v112, v173
	v_mul_f32_e32 v113, v113, v173
	v_mul_f32_e32 v114, v114, v173
	v_mul_f32_e32 v115, v115, v173
	v_mul_f32_e32 v184, 0xbfb8aa3b, v171
	v_mul_f32_e32 v116, v171, v171
	v_exp_f32_e32 v171, v172
	v_exp_f32_e32 v117, v117
	v_exp_f32_e32 v118, v118
	v_exp_f32_e32 v119, v119
	v_exp_f32_e32 v112, v112
	v_exp_f32_e32 v113, v113
	v_exp_f32_e32 v114, v114
	v_exp_f32_e32 v115, v115
	v_mul_f32_e32 v172, v108, v184
	v_mul_f32_e32 v173, v109, v184
	v_exp_f32_e32 v182, v172
	v_exp_f32_e32 v183, v173
	v_add_f32_e32 v171, 1.0, v171
	v_add_f32_e32 v117, 1.0, v117
	v_add_f32_e32 v118, 1.0, v118
	v_add_f32_e32 v119, 1.0, v119
	v_add_f32_e32 v172, 1.0, v112
	v_add_f32_e32 v173, 1.0, v113
	v_add_f32_e32 v191, 1.0, v114
	v_add_f32_e32 v192, 1.0, v115
	v_rcp_f32_e32 v112, v171
	v_rcp_f32_e32 v113, v117
	v_rcp_f32_e32 v114, v118
	v_rcp_f32_e32 v115, v119
	v_rcp_f32_e32 v118, v172
	v_rcp_f32_e32 v119, v173
	v_rcp_f32_e32 v172, v191
	v_rcp_f32_e32 v173, v192
	v_mul_f32_e32 v170, v170, v170
	v_add_f32_e32 v171, 1.0, v183
	v_rcp_f32_e32 v183, v171
	v_pk_mul_f32 v[112:113], v[170:171], v[112:113] op_sel_hi:[0,1]
	v_pk_mul_f32 v[114:115], v[170:171], v[114:115] op_sel_hi:[0,1]
	v_pk_mul_f32 v[118:119], v[170:171], v[118:119] op_sel_hi:[0,1]
	v_pk_mul_f32 v[170:171], v[170:171], v[172:173] op_sel_hi:[0,1]
	v_pk_mul_f32 v[112:113], v[176:177], v[112:113]
	v_pk_mul_f32 v[114:115], v[174:175], v[114:115]
	v_pk_mul_f32 v[118:119], v[180:181], v[118:119]
	v_pk_mul_f32 v[170:171], v[178:179], v[170:171]
	v_cvt_pk_bf16_f32 v112, v112, v113
	v_cvt_pk_bf16_f32 v113, v114, v115
	v_cvt_pk_bf16_f32 v114, v118, v119
	v_cvt_pk_bf16_f32 v115, v170, v171
	v_mul_f32_e32 v185, v110, v184
	global_store_dwordx4 v[168:169], v[112:115], off nt
	v_add_f32_e32 v117, 1.0, v182
	v_rcp_f32_e32 v182, v117
	v_mul_f32_e32 v113, v111, v184
	v_exp_f32_e32 v112, v185
	v_exp_f32_e32 v113, v113
	v_pk_mul_f32 v[108:109], v[116:117], v[182:183] op_sel_hi:[0,1]
	v_pk_mul_f32 v[104:105], v[104:105], v[108:109]
	v_add_f32_e32 v110, 1.0, v112
	v_add_f32_e32 v111, 1.0, v113
	v_rcp_f32_e32 v110, v110
	v_rcp_f32_e32 v111, v111
	v_cvt_pk_bf16_f32 v104, v104, v105
	v_mul_f32_e32 v105, v100, v184
	v_pk_mul_f32 v[108:109], v[116:117], v[110:111] op_sel_hi:[0,1]
	v_pk_mul_f32 v[106:107], v[106:107], v[108:109]
; __device__ __forceinline__ unsigned cvtpk(float lo, float hi) { f32x2_t v = {lo, hi}; bf16x2_t b = __builtin_convertvector(v, bf16x2_t); return __builtin_bit_cast(unsigned, b); }
;     __device__ __forceinline__ void operator()(const pg8::f32x4 (&acc)[2][2][4][2], const pg8::Unit& u, int wr, int wc, int fr, int fq) const {
;     ...
;             for (int m = 0; m < 4; ++m) {
;                 const int row = row0 + ai * 128 + m * 16;
;                 const float rs = rsqrtf(rsv[ai][m] * (1.f / DM) + EPS), c1 = -rs * LOG2E, rs2 = rs * rs;
;                 u32x4 w;
; #pragma unroll
;                 for (int n = 0; n < 2; ++n) {
;                     const pg8::f32x4 g = acc[ai][0][m][n], up = acc[ai][1][m][n];
;                     float o4[4];
; #pragma unroll
;                     for (int k = 0; k < 4; ++k) o4[k] = (g[k] * up[k]) * (rs2 * __builtin_amdgcn_rcpf(1.f + __builtin_amdgcn_exp2f(g[k] * c1)));
;                     w[2 * n] = cvtpk(o4[0], o4[1]); w[2 * n + 1] = cvtpk(o4[2], o4[3]);
;                 }
;                 *(u32x4*)(O + (size_t)row * FF + col0) = w;
	v_exp_f32_e32 v108, v105
	v_mul_f32_e32 v105, v101, v184
	v_exp_f32_e32 v109, v105
	v_cvt_pk_bf16_f32 v105, v106, v107
	v_add_f32_e32 v106, 1.0, v108
	v_mul_f32_e32 v108, v102, v184
	v_add_f32_e32 v107, 1.0, v109
	v_mul_f32_e32 v109, v103, v184
	v_exp_f32_e32 v108, v108
	v_exp_f32_e32 v109, v109
	v_rcp_f32_e32 v106, v106
	v_rcp_f32_e32 v107, v107
	v_add_f32_e32 v102, 1.0, v108
	v_add_f32_e32 v103, 1.0, v109
	v_rcp_f32_e32 v102, v102
	v_rcp_f32_e32 v103, v103
	v_pk_mul_f32 v[100:101], v[116:117], v[106:107] op_sel_hi:[0,1]
	v_pk_mul_f32 v[96:97], v[96:97], v[100:101]
	v_pk_mul_f32 v[100:101], v[116:117], v[102:103] op_sel_hi:[0,1]
	v_cvt_pk_bf16_f32 v106, v96, v97
	v_fmamk_f32 v96, v189, 0x3a000000, v165
	v_mul_f32_e32 v97, 0x4b800000, v96
	v_cmp_gt_f32_e32 vcc, s45, v96
	v_pk_mul_f32 v[98:99], v[98:99], v[100:101]
	s_nop 0
	v_cndmask_b32_e32 v96, v96, v97, vcc
	v_cvt_pk_bf16_f32 v107, v98, v99
	v_rsq_f32_e32 v98, v96
	v_mad_i64_i32 v[96:97], s[2:3], v144, s46, v[120:121]
	v_lshl_add_u64 v[96:97], v[96:97], 0, v[122:123]
	global_store_dwordx4 v[96:97], v[104:107], off nt
	v_mul_f32_e32 v96, 0x45800000, v98
	v_cndmask_b32_e32 v96, v98, v96, vcc
	v_mul_f32_e32 v97, 0xbfb8aa3b, v96
	v_mul_f32_e32 v98, v92, v97
	v_mul_f32_e32 v99, v93, v97
	v_exp_f32_e32 v98, v98
	v_exp_f32_e32 v99, v99
	v_mul_f32_e32 v100, v94, v97
	v_mul_f32_e32 v101, v95, v97
	v_exp_f32_e32 v100, v100
	v_exp_f32_e32 v101, v101
	v_add_f32_e32 v98, 1.0, v98
	v_add_f32_e32 v99, 1.0, v99
	v_rcp_f32_e32 v98, v98
	v_rcp_f32_e32 v99, v99
	v_add_f32_e32 v94, 1.0, v100
	v_add_f32_e32 v95, 1.0, v101
	v_rcp_f32_e32 v94, v94
	v_rcp_f32_e32 v95, v95
	v_mul_f32_e32 v96, v96, v96
	v_pk_mul_f32 v[92:93], v[96:97], v[98:99] op_sel_hi:[0,1]
	v_pk_mul_f32 v[88:89], v[88:89], v[92:93]
	v_pk_mul_f32 v[92:93], v[96:97], v[94:95] op_sel_hi:[0,1]
	v_cvt_pk_bf16_f32 v88, v88, v89
	v_mul_f32_e32 v89, v84, v97
	v_pk_mul_f32 v[90:91], v[90:91], v[92:93]
	v_exp_f32_e32 v92, v89
	v_mul_f32_e32 v89, v85, v97
	v_exp_f32_e32 v93, v89
	v_cvt_pk_bf16_f32 v89, v90, v91
	v_add_f32_e32 v90, 1.0, v92
	v_mul_f32_e32 v92, v86, v97
	v_add_f32_e32 v91, 1.0, v93
	v_mul_f32_e32 v93, v87, v97
	v_exp_f32_e32 v92, v92
	v_exp_f32_e32 v93, v93
	v_rcp_f32_e32 v90, v90
	v_rcp_f32_e32 v91, v91
	v_add_f32_e32 v86, 1.0, v92
	v_add_f32_e32 v87, 1.0, v93
	v_rcp_f32_e32 v86, v86
	v_rcp_f32_e32 v87, v87
	v_pk_mul_f32 v[84:85], v[96:97], v[90:91] op_sel_hi:[0,1]
	v_pk_mul_f32 v[80:81], v[80:81], v[84:85]
	v_pk_mul_f32 v[84:85], v[96:97], v[86:87] op_sel_hi:[0,1]
	v_cvt_pk_bf16_f32 v90, v80, v81
	v_fmamk_f32 v80, v190, 0x3a000000, v165
	v_mul_f32_e32 v81, 0x4b800000, v80
	v_cmp_gt_f32_e32 vcc, s45, v80
	v_pk_mul_f32 v[82:83], v[82:83], v[84:85]
	s_nop 0
	v_cndmask_b32_e32 v80, v80, v81, vcc
	v_cvt_pk_bf16_f32 v91, v82, v83
	v_rsq_f32_e32 v82, v80
	v_mad_i64_i32 v[80:81], s[2:3], v126, s46, v[120:121]
	v_lshl_add_u64 v[80:81], v[80:81], 0, v[122:123]
	global_store_dwordx4 v[80:81], v[88:91], off nt
	v_mul_f32_e32 v80, 0x45800000, v82
	v_cndmask_b32_e32 v80, v82, v80, vcc
	v_mul_f32_e32 v81, 0xbfb8aa3b, v80
	v_mul_f32_e32 v82, v76, v81
	v_mul_f32_e32 v83, v77, v81
	v_exp_f32_e32 v82, v82
	v_exp_f32_e32 v83, v83
	v_mul_f32_e32 v84, v78, v81
	v_mul_f32_e32 v85, v79, v81
	v_exp_f32_e32 v84, v84
	v_exp_f32_e32 v85, v85
	v_add_f32_e32 v82, 1.0, v82
	v_add_f32_e32 v83, 1.0, v83
	v_rcp_f32_e32 v82, v82
	v_rcp_f32_e32 v83, v83
	v_add_f32_e32 v78, 1.0, v84
	v_add_f32_e32 v79, 1.0, v85
	v_rcp_f32_e32 v78, v78
	v_rcp_f32_e32 v79, v79
	v_mul_f32_e32 v80, v80, v80
	v_pk_mul_f32 v[76:77], v[80:81], v[82:83] op_sel_hi:[0,1]
	v_pk_mul_f32 v[72:73], v[72:73], v[76:77]
	v_pk_mul_f32 v[76:77], v[80:81], v[78:79] op_sel_hi:[0,1]
	v_cvt_pk_bf16_f32 v72, v72, v73
	v_mul_f32_e32 v73, v68, v81
	v_pk_mul_f32 v[74:75], v[74:75], v[76:77]
	v_exp_f32_e32 v76, v73
	v_mul_f32_e32 v73, v69, v81
	v_exp_f32_e32 v77, v73
	v_cvt_pk_bf16_f32 v73, v74, v75
	v_add_f32_e32 v74, 1.0, v76
	v_mul_f32_e32 v76, v70, v81
	v_add_f32_e32 v75, 1.0, v77
	v_mul_f32_e32 v77, v71, v81
	v_exp_f32_e32 v76, v76
	v_exp_f32_e32 v77, v77
	v_rcp_f32_e32 v74, v74
	v_rcp_f32_e32 v75, v75
	v_add_f32_e32 v70, 1.0, v76
	v_add_f32_e32 v71, 1.0, v77
	v_rcp_f32_e32 v70, v70
	v_rcp_f32_e32 v71, v71
	v_pk_mul_f32 v[68:69], v[80:81], v[74:75] op_sel_hi:[0,1]
	v_pk_mul_f32 v[64:65], v[64:65], v[68:69]
	v_pk_mul_f32 v[68:69], v[80:81], v[70:71] op_sel_hi:[0,1]
	v_cvt_pk_bf16_f32 v74, v64, v65
	v_fmamk_f32 v64, v187, 0x3a000000, v165
	v_mul_f32_e32 v65, 0x4b800000, v64
	v_cmp_gt_f32_e32 vcc, s45, v64
	v_pk_mul_f32 v[66:67], v[66:67], v[68:69]
	s_nop 0
	v_cndmask_b32_e32 v64, v64, v65, vcc
	v_cvt_pk_bf16_f32 v75, v66, v67
	v_rsq_f32_e32 v66, v64
	v_mad_i64_i32 v[64:65], s[2:3], v124, s46, v[120:121]
	v_lshl_add_u64 v[64:65], v[64:65], 0, v[122:123]
	global_store_dwordx4 v[64:65], v[72:75], off nt
	v_mul_f32_e32 v64, 0x45800000, v66
	v_cndmask_b32_e32 v64, v66, v64, vcc
	v_mul_f32_e32 v65, 0xbfb8aa3b, v64
	v_mul_f32_e32 v66, v60, v65
	v_mul_f32_e32 v67, v61, v65
	v_exp_f32_e32 v66, v66
	v_exp_f32_e32 v67, v67
	v_mul_f32_e32 v68, v62, v65
	v_mul_f32_e32 v69, v63, v65
	v_exp_f32_e32 v68, v68
	v_exp_f32_e32 v69, v69
	v_add_f32_e32 v66, 1.0, v66
	v_add_f32_e32 v67, 1.0, v67
	v_rcp_f32_e32 v66, v66
	v_rcp_f32_e32 v67, v67
	v_add_f32_e32 v62, 1.0, v68
	v_add_f32_e32 v63, 1.0, v69
	v_rcp_f32_e32 v62, v62
	v_rcp_f32_e32 v63, v63
	v_mul_f32_e32 v64, v64, v64
	v_pk_mul_f32 v[60:61], v[64:65], v[66:67] op_sel_hi:[0,1]
	v_pk_mul_f32 v[56:57], v[56:57], v[60:61]
	v_pk_mul_f32 v[60:61], v[64:65], v[62:63] op_sel_hi:[0,1]
	v_cvt_pk_bf16_f32 v56, v56, v57
	v_mul_f32_e32 v57, v52, v65
	v_pk_mul_f32 v[58:59], v[58:59], v[60:61]
; __device__ __forceinline__ unsigned cvtpk(float lo, float hi) { f32x2_t v = {lo, hi}; bf16x2_t b = __builtin_convertvector(v, bf16x2_t); return __builtin_bit_cast(unsigned, b); }
;     __device__ __forceinline__ void operator()(const pg8::f32x4 (&acc)[2][2][4][2], const pg8::Unit& u, int wr, int wc, int fr, int fq) const {
;     ...
;             for (int m = 0; m < 4; ++m) {
;                 const int row = row0 + ai * 128 + m * 16;
;                 const float rs = rsqrtf(rsv[ai][m] * (1.f / DM) + EPS), c1 = -rs * LOG2E, rs2 = rs * rs;
;                 u32x4 w;
; #pragma unroll
;                 for (int n = 0; n < 2; ++n) {
;                     const pg8::f32x4 g = acc[ai][0][m][n], up = acc[ai][1][m][n];
;                     float o4[4];
; #pragma unroll
;                     for (int k = 0; k < 4; ++k) o4[k] = (g[k] * up[k]) * (rs2 * __builtin_amdgcn_rcpf(1.f + __builtin_amdgcn_exp2f(g[k] * c1)));
;                     w[2 * n] = cvtpk(o4[0], o4[1]); w[2 * n + 1] = cvtpk(o4[2], o4[3]);
;                 }
;                 *(u32x4*)(O + (size_t)row * FF + col0) = w;
	v_exp_f32_e32 v60, v57
	v_mul_f32_e32 v57, v53, v65
	v_exp_f32_e32 v61, v57
	v_cvt_pk_bf16_f32 v57, v58, v59
	v_add_f32_e32 v58, 1.0, v60
	v_mul_f32_e32 v60, v54, v65
	v_add_f32_e32 v59, 1.0, v61
	v_mul_f32_e32 v61, v55, v65
	v_exp_f32_e32 v60, v60
	v_exp_f32_e32 v61, v61
	v_rcp_f32_e32 v58, v58
	v_rcp_f32_e32 v59, v59
	v_add_f32_e32 v54, 1.0, v60
	v_add_f32_e32 v55, 1.0, v61
	v_rcp_f32_e32 v54, v54
	v_rcp_f32_e32 v55, v55
	v_pk_mul_f32 v[52:53], v[64:65], v[58:59] op_sel_hi:[0,1]
	v_pk_mul_f32 v[48:49], v[48:49], v[52:53]
	v_pk_mul_f32 v[52:53], v[64:65], v[54:55] op_sel_hi:[0,1]
	v_cvt_pk_bf16_f32 v58, v48, v49
	v_fmamk_f32 v48, v188, 0x3a000000, v165
	v_mul_f32_e32 v49, 0x4b800000, v48
	v_cmp_gt_f32_e32 vcc, s45, v48
	v_pk_mul_f32 v[50:51], v[50:51], v[52:53]
	s_nop 0
	v_cndmask_b32_e32 v48, v48, v49, vcc
	v_cvt_pk_bf16_f32 v59, v50, v51
	v_rsq_f32_e32 v50, v48
	v_mad_i64_i32 v[48:49], s[2:3], v186, s46, v[120:121]
	v_lshl_add_u64 v[48:49], v[48:49], 0, v[122:123]
	global_store_dwordx4 v[48:49], v[56:59], off nt
	v_mul_f32_e32 v48, 0x45800000, v50
	v_cndmask_b32_e32 v48, v50, v48, vcc
	v_mul_f32_e32 v49, 0xbfb8aa3b, v48
	v_mul_f32_e32 v50, v44, v49
	v_mul_f32_e32 v51, v45, v49
	v_exp_f32_e32 v50, v50
	v_exp_f32_e32 v51, v51
	v_mul_f32_e32 v52, v46, v49
	v_mul_f32_e32 v53, v47, v49
	v_exp_f32_e32 v52, v52
	v_exp_f32_e32 v53, v53
	v_add_f32_e32 v50, 1.0, v50
	v_add_f32_e32 v51, 1.0, v51
	v_rcp_f32_e32 v50, v50
	v_rcp_f32_e32 v51, v51
	v_add_f32_e32 v46, 1.0, v52
	v_add_f32_e32 v47, 1.0, v53
	v_rcp_f32_e32 v46, v46
	v_rcp_f32_e32 v47, v47
	v_mul_f32_e32 v48, v48, v48
	v_pk_mul_f32 v[44:45], v[48:49], v[50:51] op_sel_hi:[0,1]
	v_pk_mul_f32 v[40:41], v[40:41], v[44:45]
	v_pk_mul_f32 v[44:45], v[48:49], v[46:47] op_sel_hi:[0,1]
	v_cvt_pk_bf16_f32 v40, v40, v41
	v_mul_f32_e32 v41, v36, v49
	v_pk_mul_f32 v[42:43], v[42:43], v[44:45]
	v_exp_f32_e32 v44, v41
	v_mul_f32_e32 v41, v37, v49
	v_exp_f32_e32 v45, v41
	v_cvt_pk_bf16_f32 v41, v42, v43
	v_add_f32_e32 v42, 1.0, v44
	v_mul_f32_e32 v44, v38, v49
	v_add_f32_e32 v43, 1.0, v45
	v_mul_f32_e32 v45, v39, v49
	v_exp_f32_e32 v44, v44
	v_exp_f32_e32 v45, v45
	v_rcp_f32_e32 v42, v42
	v_rcp_f32_e32 v43, v43
	v_add_f32_e32 v38, 1.0, v44
	v_add_f32_e32 v39, 1.0, v45
	v_rcp_f32_e32 v38, v38
	v_rcp_f32_e32 v39, v39
	v_pk_mul_f32 v[36:37], v[48:49], v[42:43] op_sel_hi:[0,1]
	v_pk_mul_f32 v[32:33], v[32:33], v[36:37]
	v_pk_mul_f32 v[36:37], v[48:49], v[38:39] op_sel_hi:[0,1]
	v_cvt_pk_bf16_f32 v42, v32, v33
	v_fmamk_f32 v32, v127, 0x3a000000, v165
	v_mul_f32_e32 v33, 0x4b800000, v32
	v_cmp_gt_f32_e32 vcc, s45, v32
	v_pk_mul_f32 v[34:35], v[34:35], v[36:37]
	s_nop 0
	v_cndmask_b32_e32 v32, v32, v33, vcc
	v_cvt_pk_bf16_f32 v43, v34, v35
	v_rsq_f32_e32 v34, v32
	v_mad_i64_i32 v[32:33], s[2:3], v167, s46, v[120:121]
	v_lshl_add_u64 v[32:33], v[32:33], 0, v[122:123]
	global_store_dwordx4 v[32:33], v[40:43], off nt
	v_mul_f32_e32 v32, 0x45800000, v34
	v_cndmask_b32_e32 v32, v34, v32, vcc
	v_mul_f32_e32 v33, 0xbfb8aa3b, v32
	v_mul_f32_e32 v34, v28, v33
	v_mul_f32_e32 v35, v29, v33
	v_exp_f32_e32 v34, v34
	v_exp_f32_e32 v35, v35
	v_mul_f32_e32 v36, v30, v33
	v_mul_f32_e32 v37, v31, v33
	v_exp_f32_e32 v36, v36
	v_exp_f32_e32 v37, v37
	v_add_f32_e32 v34, 1.0, v34
	v_add_f32_e32 v35, 1.0, v35
	v_rcp_f32_e32 v34, v34
	v_rcp_f32_e32 v35, v35
	v_add_f32_e32 v30, 1.0, v36
	v_add_f32_e32 v31, 1.0, v37
	v_rcp_f32_e32 v30, v30
	v_rcp_f32_e32 v31, v31
	v_mul_f32_e32 v32, v32, v32
	v_pk_mul_f32 v[28:29], v[32:33], v[34:35] op_sel_hi:[0,1]
	v_pk_mul_f32 v[24:25], v[24:25], v[28:29]
	v_pk_mul_f32 v[28:29], v[32:33], v[30:31] op_sel_hi:[0,1]
	v_cvt_pk_bf16_f32 v24, v24, v25
	v_mul_f32_e32 v25, v20, v33
	v_pk_mul_f32 v[26:27], v[26:27], v[28:29]
	v_exp_f32_e32 v28, v25
	v_mul_f32_e32 v25, v21, v33
	v_exp_f32_e32 v29, v25
	v_cvt_pk_bf16_f32 v25, v26, v27
	v_add_f32_e32 v26, 1.0, v28
	v_mul_f32_e32 v28, v22, v33
	v_add_f32_e32 v27, 1.0, v29
	v_mul_f32_e32 v29, v23, v33
	v_exp_f32_e32 v28, v28
	v_exp_f32_e32 v29, v29
	v_rcp_f32_e32 v26, v26
	v_rcp_f32_e32 v27, v27
	v_add_f32_e32 v22, 1.0, v28
	v_add_f32_e32 v23, 1.0, v29
	v_rcp_f32_e32 v22, v22
	v_rcp_f32_e32 v23, v23
	v_pk_mul_f32 v[20:21], v[32:33], v[26:27] op_sel_hi:[0,1]
	v_pk_mul_f32 v[16:17], v[16:17], v[20:21]
	v_pk_mul_f32 v[20:21], v[32:33], v[22:23] op_sel_hi:[0,1]
	v_cvt_pk_bf16_f32 v26, v16, v17
	v_fmamk_f32 v16, v125, 0x3a000000, v165
	v_mul_f32_e32 v17, 0x4b800000, v16
	v_cmp_gt_f32_e32 vcc, s45, v16
	v_pk_mul_f32 v[18:19], v[18:19], v[20:21]
	s_nop 0
	v_cndmask_b32_e32 v16, v16, v17, vcc
	v_cvt_pk_bf16_f32 v27, v18, v19
	v_rsq_f32_e32 v18, v16
	v_mad_i64_i32 v[16:17], s[2:3], v166, s46, v[120:121]
	v_lshl_add_u64 v[16:17], v[16:17], 0, v[122:123]
	global_store_dwordx4 v[16:17], v[24:27], off nt
	v_mul_f32_e32 v16, 0x45800000, v18
	v_cndmask_b32_e32 v16, v18, v16, vcc
	v_mul_f32_e32 v17, 0xbfb8aa3b, v16
	v_mul_f32_e32 v18, v12, v17
	v_mul_f32_e32 v19, v13, v17
	v_exp_f32_e32 v18, v18
	v_exp_f32_e32 v19, v19
	v_mul_f32_e32 v20, v14, v17
	v_mul_f32_e32 v21, v15, v17
	v_exp_f32_e32 v20, v20
	v_exp_f32_e32 v21, v21
	v_add_f32_e32 v18, 1.0, v18
	v_add_f32_e32 v19, 1.0, v19
	v_rcp_f32_e32 v18, v18
	v_rcp_f32_e32 v19, v19
	v_add_f32_e32 v14, 1.0, v20
	v_add_f32_e32 v15, 1.0, v21
	v_rcp_f32_e32 v14, v14
	v_rcp_f32_e32 v15, v15
	v_mul_f32_e32 v16, v16, v16
	v_pk_mul_f32 v[12:13], v[16:17], v[18:19] op_sel_hi:[0,1]
	v_pk_mul_f32 v[8:9], v[8:9], v[12:13]
	v_pk_mul_f32 v[12:13], v[16:17], v[14:15] op_sel_hi:[0,1]
	v_cvt_pk_bf16_f32 v8, v8, v9
	v_mul_f32_e32 v9, v4, v17
	v_pk_mul_f32 v[10:11], v[10:11], v[12:13]
	v_exp_f32_e32 v12, v9
	v_mul_f32_e32 v9, v5, v17
	v_exp_f32_e32 v13, v9
	v_cvt_pk_bf16_f32 v9, v10, v11
	v_add_f32_e32 v10, 1.0, v12
	v_mul_f32_e32 v12, v6, v17
	v_add_f32_e32 v11, 1.0, v13
	v_mul_f32_e32 v13, v7, v17
	v_exp_f32_e32 v12, v12
	v_exp_f32_e32 v13, v13
	v_rcp_f32_e32 v10, v10
	v_rcp_f32_e32 v11, v11
	v_add_f32_e32 v6, 1.0, v12
	v_add_f32_e32 v7, 1.0, v13
	v_rcp_f32_e32 v6, v6
	v_rcp_f32_e32 v7, v7
	v_pk_mul_f32 v[4:5], v[16:17], v[10:11] op_sel_hi:[0,1]
	v_pk_mul_f32 v[0:1], v[0:1], v[4:5]
	s_andn2_b64 vcc, exec, s[0:1]
	v_pk_mul_f32 v[4:5], v[16:17], v[6:7] op_sel_hi:[0,1]
	v_pk_mul_f32 v[2:3], v[2:3], v[4:5]
	v_cvt_pk_bf16_f32 v10, v0, v1
	v_mad_i64_i32 v[0:1], s[2:3], v145, s46, v[120:121]
	v_cvt_pk_bf16_f32 v11, v2, v3
	v_lshl_add_u64 v[0:1], v[0:1], 0, v[122:123]
	s_mov_b64 s[0:1], -1
	global_store_dwordx4 v[0:1], v[8:11], off nt
	s_cbranch_vccnz .LBB0_1072
	s_andn2_b64 vcc, exec, s[4:5]
	s_cbranch_vccnz .LBB0_1071
	s_barrier
	s_branch .LBB0_1071
